# hyena prompt path: 8 filter taps per thread via batched branch-free loads (was 8+ serialized load/wait pairs per order)
# baseline (speedup 1.0000x reference)
.LBB0_477:
	s_or_b64 exec, exec, s[0:1]
	s_waitcnt lgkmcnt(0)
	s_barrier
	ds_read_b128 v[0:3], v112 offset:25216
	ds_read_b128 v[4:7], v112 offset:25232
	ds_read_b128 v[8:11], v112 offset:25248
	ds_read_b128 v[12:15], v112 offset:25264
	s_mov_b32 s0, 0x358637bd
	s_waitcnt lgkmcnt(3)
	v_mov_b32_e32 v74, v0
	s_mov_b32 s63, s96
	s_waitcnt lgkmcnt(1)
	v_mov_b32_e32 v75, v8
	v_pk_add_f32 v[74:75], v[74:75], 0 op_sel_hi:[1,0]
	v_mov_b32_e32 v8, v1
	v_pk_add_f32 v[0:1], v[74:75], v[8:9]
	v_mov_b32_e32 v8, v2
	v_mov_b32_e32 v9, v10
	v_pk_add_f32 v[0:1], v[0:1], v[8:9]
	v_mov_b32_e32 v10, v3
	v_pk_add_f32 v[0:1], v[0:1], v[10:11]
	v_mov_b32_e32 v2, v4
	s_waitcnt lgkmcnt(0)
	v_mov_b32_e32 v3, v12
	v_pk_add_f32 v[0:1], v[0:1], v[2:3]
	v_mov_b32_e32 v12, v5
	v_pk_add_f32 v[0:1], v[0:1], v[12:13]
	v_mov_b32_e32 v2, v6
	v_mov_b32_e32 v3, v14
	v_pk_add_f32 v[0:1], v[0:1], v[2:3]
	v_mov_b32_e32 v14, v7
	v_pk_add_f32 v[0:1], v[0:1], v[14:15]
	v_readlane_b32 s72, v254, 10
	v_pk_add_f32 v[0:1], v[0:1], s[0:1] op_sel_hi:[1,0]
	v_readlane_b32 s78, v254, 16
	v_div_scale_f32 v2, s[0:1], v1, v1, 1.0
	v_rcp_f32_e32 v3, v2
	v_readlane_b32 s79, v254, 17
	v_readlane_b32 s4, v254, 41
	v_readlane_b32 s5, v254, 42
	v_fma_f32 v4, -v2, v3, 1.0
	v_fmac_f32_e32 v3, v4, v3
	v_div_scale_f32 v4, vcc, 1.0, v1, 1.0
	v_mul_f32_e32 v5, v4, v3
	v_fma_f32 v6, -v2, v5, v4
	v_fmac_f32_e32 v5, v6, v3
	v_fma_f32 v2, -v2, v5, v4
	v_div_fmas_f32 v2, v2, v3, v5
	v_div_fixup_f32 v1, v2, v1, 1.0
	v_div_scale_f32 v2, s[0:1], v0, v0, 1.0
	v_rcp_f32_e32 v3, v2
	s_lshl_b64 s[0:1], s[62:63], 2
	s_add_u32 s0, s78, s0
	s_addc_u32 s1, s79, s1
	v_fma_f32 v4, -v2, v3, 1.0
	v_fmac_f32_e32 v3, v4, v3
	v_div_scale_f32 v4, vcc, 1.0, v0, 1.0
	v_mul_f32_e32 v5, v4, v3
	v_fma_f32 v6, -v2, v5, v4
	v_fmac_f32_e32 v5, v6, v3
	v_fma_f32 v2, -v2, v5, v4
	v_div_fmas_f32 v2, v2, v3, v5
	v_div_fixup_f32 v0, v2, v0, 1.0
	global_load_dword v2, v112, s[0:1]
	s_lshl_b64 s[0:1], s[62:63], 10
	s_add_u32 s62, s4, s0
	s_addc_u32 s63, s5, s1
	s_lshl_b32 s0, s64, 8
	s_mov_b32 s1, s96
	s_lshl_b64 s[0:1], s[0:1], 2
	s_add_u32 s64, s4, s0
	s_addc_u32 s65, s5, s1
	v_mov_b32_e32 v3, 0
	v_mov_b32_e32 v4, 0
	v_readlane_b32 s73, v254, 11
	v_readlane_b32 s74, v254, 12
	v_readlane_b32 s75, v254, 13
	v_readlane_b32 s76, v254, 14
	v_readlane_b32 s77, v254, 15
	v_readlane_b32 s80, v254, 18
	v_readlane_b32 s81, v254, 19
	v_readlane_b32 s82, v254, 20
	v_readlane_b32 s83, v254, 21
	v_readlane_b32 s84, v254, 22
	v_readlane_b32 s85, v254, 23
	v_readlane_b32 s86, v254, 24
	v_readlane_b32 s87, v254, 25
	s_sub_u32 s0, s64, s62
	v_and_b32_e32 v160, 63, v192
	v_lshrrev_b32_e32 v161, 6, v192
	v_lshl_add_u32 v160, v160, 3, v161
	v_sub_u32_e32 v142, 0x100, v160
	v_sub_u32_e32 v161, 0, v142
	v_max_i32_e32 v161, v142, v161
	v_ashrrev_i32_e32 v162, 31, v142
	v_and_b32_e32 v162, s0, v162
	v_lshl_add_u32 v161, v161, 2, v162
	global_load_dword v150, v161, s[62:63]
	v_add_u32_e32 v143, -1, v142
	v_sub_u32_e32 v161, 0, v143
	v_max_i32_e32 v161, v143, v161
	v_ashrrev_i32_e32 v162, 31, v143
	v_and_b32_e32 v162, s0, v162
	v_lshl_add_u32 v161, v161, 2, v162
	global_load_dword v151, v161, s[62:63]
	v_add_u32_e32 v144, -2, v142
	v_sub_u32_e32 v161, 0, v144
	v_max_i32_e32 v161, v144, v161
	v_ashrrev_i32_e32 v162, 31, v144
	v_and_b32_e32 v162, s0, v162
	v_lshl_add_u32 v161, v161, 2, v162
	global_load_dword v152, v161, s[62:63]
	v_add_u32_e32 v145, -3, v142
	v_sub_u32_e32 v161, 0, v145
	v_max_i32_e32 v161, v145, v161
	v_ashrrev_i32_e32 v162, 31, v145
	v_and_b32_e32 v162, s0, v162
	v_lshl_add_u32 v161, v161, 2, v162
	global_load_dword v153, v161, s[62:63]
	v_add_u32_e32 v146, -4, v142
	v_sub_u32_e32 v161, 0, v146
	v_max_i32_e32 v161, v146, v161
	v_ashrrev_i32_e32 v162, 31, v146
	v_and_b32_e32 v162, s0, v162
	v_lshl_add_u32 v161, v161, 2, v162
	global_load_dword v154, v161, s[62:63]
	v_add_u32_e32 v147, -5, v142
	v_sub_u32_e32 v161, 0, v147
	v_max_i32_e32 v161, v147, v161
	v_ashrrev_i32_e32 v162, 31, v147
	v_and_b32_e32 v162, s0, v162
	v_lshl_add_u32 v161, v161, 2, v162
	global_load_dword v155, v161, s[62:63]
	v_add_u32_e32 v148, -6, v142
	v_sub_u32_e32 v161, 0, v148
	v_max_i32_e32 v161, v148, v161
	v_ashrrev_i32_e32 v162, 31, v148
	v_and_b32_e32 v162, s0, v162
	v_lshl_add_u32 v161, v161, 2, v162
	global_load_dword v156, v161, s[62:63]
	v_add_u32_e32 v149, -7, v142
	v_sub_u32_e32 v161, 0, v149
	v_max_i32_e32 v161, v149, v161
	v_ashrrev_i32_e32 v162, 31, v149
	v_and_b32_e32 v162, s0, v162
	v_lshl_add_u32 v161, v161, 2, v162
	global_load_dword v157, v161, s[62:63]
	global_load_dword v158, v112, s[62:63]
	global_load_dword v159, v112, s[64:65]
	s_waitcnt vmcnt(0)
	v_mul_f32_e32 v158, v0, v158
	v_mul_f32_e32 v159, v1, v159
	v_add_f32_e32 v158, v158, v159
	v_add_f32_e32 v158, v2, v158
	v_cmp_lt_i32_e32 vcc, 0, v142
	v_add_u32_e32 v161, 0xff, v142
	s_nop 0
	v_cndmask_b32_e32 v160, v1, v0, vcc
	v_cmp_eq_u32_e32 vcc, 0, v142
	v_mul_f32_e32 v150, v160, v150
	s_nop 0
	v_cndmask_b32_e32 v150, v150, v158, vcc
	v_cmp_gt_u32_e32 vcc, 0x1ff, v161
	s_nop 1
	v_cndmask_b32_e32 v150, 0, v150, vcc
	v_cmp_lt_i32_e32 vcc, 0, v143
	v_add_u32_e32 v161, 0xff, v143
	s_nop 0
	v_cndmask_b32_e32 v160, v1, v0, vcc
	v_cmp_eq_u32_e32 vcc, 0, v143
	v_mul_f32_e32 v151, v160, v151
	s_nop 0
	v_cndmask_b32_e32 v151, v151, v158, vcc
	v_cmp_gt_u32_e32 vcc, 0x1ff, v161
	s_nop 1
	v_cndmask_b32_e32 v151, 0, v151, vcc
	v_cmp_lt_i32_e32 vcc, 0, v144
	v_add_u32_e32 v161, 0xff, v144
	s_nop 0
	v_cndmask_b32_e32 v160, v1, v0, vcc
	v_cmp_eq_u32_e32 vcc, 0, v144
	v_mul_f32_e32 v152, v160, v152
	s_nop 0
	v_cndmask_b32_e32 v152, v152, v158, vcc
	v_cmp_gt_u32_e32 vcc, 0x1ff, v161
	s_nop 1
	v_cndmask_b32_e32 v152, 0, v152, vcc
	v_cmp_lt_i32_e32 vcc, 0, v145
	v_add_u32_e32 v161, 0xff, v145
	s_nop 0
	v_cndmask_b32_e32 v160, v1, v0, vcc
	v_cmp_eq_u32_e32 vcc, 0, v145
	v_mul_f32_e32 v153, v160, v153
	s_nop 0
	v_cndmask_b32_e32 v153, v153, v158, vcc
	v_cmp_gt_u32_e32 vcc, 0x1ff, v161
	s_nop 1
	v_cndmask_b32_e32 v153, 0, v153, vcc
	v_cmp_lt_i32_e32 vcc, 0, v146
	v_add_u32_e32 v161, 0xff, v146
	s_nop 0
	v_cndmask_b32_e32 v160, v1, v0, vcc
	v_cmp_eq_u32_e32 vcc, 0, v146
	v_mul_f32_e32 v154, v160, v154
	s_nop 0
	v_cndmask_b32_e32 v154, v154, v158, vcc
	v_cmp_gt_u32_e32 vcc, 0x1ff, v161
	s_nop 1
	v_cndmask_b32_e32 v154, 0, v154, vcc
	v_cmp_lt_i32_e32 vcc, 0, v147
	v_add_u32_e32 v161, 0xff, v147
	s_nop 0
	v_cndmask_b32_e32 v160, v1, v0, vcc
	v_cmp_eq_u32_e32 vcc, 0, v147
	v_mul_f32_e32 v155, v160, v155
	s_nop 0
	v_cndmask_b32_e32 v155, v155, v158, vcc
	v_cmp_gt_u32_e32 vcc, 0x1ff, v161
	s_nop 1
	v_cndmask_b32_e32 v155, 0, v155, vcc
	v_cmp_lt_i32_e32 vcc, 0, v148
	v_add_u32_e32 v161, 0xff, v148
	s_nop 0
	v_cndmask_b32_e32 v160, v1, v0, vcc
	v_cmp_eq_u32_e32 vcc, 0, v148
	v_mul_f32_e32 v156, v160, v156
	s_nop 0
	v_cndmask_b32_e32 v156, v156, v158, vcc
	v_cmp_gt_u32_e32 vcc, 0x1ff, v161
	s_nop 1
	v_cndmask_b32_e32 v156, 0, v156, vcc
	v_cmp_lt_i32_e32 vcc, 0, v149
	v_add_u32_e32 v161, 0xff, v149
	s_nop 0
	v_cndmask_b32_e32 v160, v1, v0, vcc
	v_cmp_eq_u32_e32 vcc, 0, v149
	v_mul_f32_e32 v157, v160, v157
	s_nop 0
	v_cndmask_b32_e32 v157, v157, v158, vcc
	v_cmp_gt_u32_e32 vcc, 0x1ff, v161
	s_nop 1
	v_cndmask_b32_e32 v157, 0, v157, vcc
	v_cvt_pk_bf16_f32 v0, v150, v151
	v_cvt_pk_bf16_f32 v1, v152, v153
	v_cvt_pk_bf16_f32 v2, v154, v155
	v_cvt_pk_bf16_f32 v3, v156, v157
	s_and_b64 vcc, exec, s[60:61]
	ds_write_b128 v73, v[0:3]
	s_cbranch_vccz .LBB0_559
	global_load_dwordx4 v[0:3], v[52:53], off
	v_add_u32_e32 v4, v17, v67
	s_waitcnt vmcnt(0)
	ds_write_b128 v4, v[0:3] offset:8320
	global_load_dwordx4 v[0:3], v[54:55], off
	v_add_u32_e32 v4, v17, v64
	s_waitcnt vmcnt(0)
	ds_write_b128 v4, v[0:3] offset:8320
